# attention unit epilogue: all 8 gate loads issued up front into dead O registers, counted vmcnt waits (was one exposed round trip per iteration)
# speedup vs baseline: 1.0061x; 1.0061x over previous
; __device__ __forceinline__ bf16_t f2bf(float f) { return (bf16_t)(cvt_pk_bf16(f, 0.f) & 0xffffu); }
; __device__ __forceinline__ int crow(int r, int hi) { return (r & 3) + 8 * (r >> 2) + 4 * hi; }
; __device__ __forceinline__ void attn_unit_dma(const bf16_t* __restrict__ Qb, const bf16_t* __restrict__ Kh, const bf16_t* __restrict__ Vh, int seq, char* lds, LAS unsigned char* ldsl, ...
;     ...
;   { auto rr_ = __builtin_amdgcn_permlane32_swap(__float_as_uint(l_reg), __float_as_uint(l_reg), false, false); l_reg = __uint_as_float(rr_[0]) + __uint_as_float(rr_[1]); }
;   if (hi == 0) li_l[r32] = l_reg; asm volatile("s_waitcnt vmcnt(0) lgkmcnt(0)" ::: "memory");
;   __syncthreads();
;   {
;     constexpr int RS = 272;
;     int tid_e = threadIdx.x; asm volatile("" : "+v"(tid_e));
;     const int wid = tid_e >> 6, lane = tid_e & 63, r32 = lane & 31, hi = lane >> 5;
;     char* Ost = lds + wid * (32 * RS);
; #pragma unroll
;     for (int r = 0; r < 16; ++r) { const int rw = crow(r, hi); const float rl = __builtin_amdgcn_rcpf(li_l[rw]);
; #pragma unroll
;       for (int d0 = 0; d0 < 4; ++d0) *(bf16_t*)(Ost + rw * RS + (d0 * 32 + r32) * 2) = f2bf(o[d0][r] * rl); }
;     asm volatile("s_waitcnt lgkmcnt(0)" ::: "memory");
.LBB0_813:
	s_or_b64 exec, exec, s[6:7]
	v_mov_b32_e32 v66, v0
	s_waitcnt vmcnt(0) lgkmcnt(0)
	s_waitcnt vmcnt(0) lgkmcnt(0)
	s_barrier
	s_movk_i32 s6, 0x2200
	v_lshrrev_b32_e32 v67, 3, v66
	v_and_b32_e32 v67, 4, v67
	v_lshl_add_u32 v68, v67, 2, s10
	ds_read_b32 v69, v68
	v_ashrrev_i32_e32 v70, 6, v66
	v_mul_lo_u32 v71, v70, s6
	v_lshlrev_b32_e32 v72, 1, v66
	v_add_u32_e32 v71, 0, v71
	s_waitcnt lgkmcnt(0)
	v_rcp_f32_e32 v69, v69
	v_and_b32_e32 v72, 62, v72
	v_mul_u32_u24_e32 v67, 0x110, v67
	v_add3_u32 v67, v71, v67, v72
	v_mul_f32_e32 v2, v2, v69
	v_cvt_pk_bf16_f32 v2, v2, v115
	ds_write_b16 v67, v2
	v_mul_f32_e32 v2, v18, v69
	v_cvt_pk_bf16_f32 v2, v2, v115
	ds_write_b16 v67, v2 offset:64
	v_mul_f32_e32 v2, v34, v69
	v_cvt_pk_bf16_f32 v2, v2, v115
	ds_write_b16 v67, v2 offset:128
	v_mul_f32_e32 v2, v50, v69
	v_cvt_pk_bf16_f32 v2, v2, v115
	ds_read_b32 v18, v68 offset:4
	ds_write_b16 v67, v2 offset:192
	s_mul_i32 s6, s21, 0xa400
	s_mul_hi_u32 s7, s20, 0xa400
	s_add_i32 s7, s7, s6
	s_waitcnt lgkmcnt(1)
	v_rcp_f32_e32 v18, v18
	s_mul_i32 s6, s20, 0xa400
	s_add_u32 s6, s77, s6
	s_addc_u32 s7, s62, s7
	v_mul_f32_e32 v2, v3, v18
	v_cvt_pk_bf16_f32 v2, v2, v115
	ds_write_b16 v67, v2 offset:272
	v_mul_f32_e32 v2, v19, v18
	v_cvt_pk_bf16_f32 v2, v2, v115
	ds_write_b16 v67, v2 offset:336
	v_mul_f32_e32 v2, v35, v18
	v_cvt_pk_bf16_f32 v2, v2, v115
	ds_write_b16 v67, v2 offset:400
	v_mul_f32_e32 v2, v51, v18
	v_cvt_pk_bf16_f32 v2, v2, v115
	ds_read_b32 v3, v68 offset:8
	ds_write_b16 v67, v2 offset:464
	s_lshl_b32 s10, s36, 8
	s_add_u32 s6, s6, s10
	s_addc_u32 s7, s7, 0
	s_waitcnt lgkmcnt(1)
	v_rcp_f32_e32 v3, v3
	s_nop 0
	v_mul_f32_e32 v2, v4, v3
	v_cvt_pk_bf16_f32 v2, v2, v115
	ds_write_b16 v67, v2 offset:544
	v_mul_f32_e32 v2, v20, v3
	v_cvt_pk_bf16_f32 v2, v2, v115
	ds_write_b16 v67, v2 offset:608
	v_mul_f32_e32 v2, v36, v3
	v_cvt_pk_bf16_f32 v2, v2, v115
	ds_write_b16 v67, v2 offset:672
	v_mul_f32_e32 v2, v52, v3
	v_cvt_pk_bf16_f32 v2, v2, v115
	ds_read_b32 v3, v68 offset:12
	ds_write_b16 v67, v2 offset:736
	s_waitcnt lgkmcnt(1)
	v_rcp_f32_e32 v3, v3
	s_nop 0
	v_mul_f32_e32 v2, v5, v3
	v_cvt_pk_bf16_f32 v2, v2, v115
	ds_write_b16 v67, v2 offset:816
	v_mul_f32_e32 v2, v21, v3
	v_cvt_pk_bf16_f32 v2, v2, v115
	ds_write_b16 v67, v2 offset:880
	v_mul_f32_e32 v2, v37, v3
	v_cvt_pk_bf16_f32 v2, v2, v115
	ds_write_b16 v67, v2 offset:944
	v_mul_f32_e32 v2, v53, v3
	v_cvt_pk_bf16_f32 v2, v2, v115
	ds_read_b32 v3, v68 offset:32
	ds_write_b16 v67, v2 offset:1008
	v_bfe_u32 v5, v66, 4, 2
	v_lshl_or_b32 v4, v70, 5, v5
	v_mul_u32_u24_e32 v5, 0x110, v5
	s_waitcnt lgkmcnt(1)
	v_rcp_f32_e32 v3, v3
	s_nop 0
	v_mul_f32_e32 v2, v6, v3
	v_cvt_pk_bf16_f32 v2, v2, v115
	ds_write_b16 v67, v2 offset:2176
	v_mul_f32_e32 v2, v22, v3
	v_cvt_pk_bf16_f32 v2, v2, v115
	ds_write_b16 v67, v2 offset:2240
	v_mul_f32_e32 v2, v38, v3
	v_cvt_pk_bf16_f32 v2, v2, v115
	ds_write_b16 v67, v2 offset:2304
	v_mul_f32_e32 v2, v54, v3
	v_cvt_pk_bf16_f32 v2, v2, v115
	ds_read_b32 v3, v68 offset:36
	ds_write_b16 v67, v2 offset:2368
	v_or_b32_e32 v22, 4, v4
	s_waitcnt lgkmcnt(1)
	v_rcp_f32_e32 v3, v3
	s_nop 0
	v_mul_f32_e32 v2, v7, v3
	v_cvt_pk_bf16_f32 v2, v2, v115
	ds_write_b16 v67, v2 offset:2448
	v_mul_f32_e32 v2, v23, v3
	v_cvt_pk_bf16_f32 v2, v2, v115
	ds_write_b16 v67, v2 offset:2512
	v_mul_f32_e32 v2, v39, v3
	v_cvt_pk_bf16_f32 v2, v2, v115
	ds_write_b16 v67, v2 offset:2576
	v_mul_f32_e32 v2, v55, v3
	v_cvt_pk_bf16_f32 v2, v2, v115
	ds_read_b32 v3, v68 offset:40
	ds_write_b16 v67, v2 offset:2640
	s_waitcnt lgkmcnt(1)
	v_rcp_f32_e32 v3, v3
	s_nop 0
	v_mul_f32_e32 v2, v8, v3
	v_cvt_pk_bf16_f32 v2, v2, v115
	ds_write_b16 v67, v2 offset:2720
	v_mul_f32_e32 v2, v24, v3
	v_cvt_pk_bf16_f32 v2, v2, v115
	ds_write_b16 v67, v2 offset:2784
	v_mul_f32_e32 v2, v40, v3
	v_cvt_pk_bf16_f32 v2, v2, v115
	ds_write_b16 v67, v2 offset:2848
	v_mul_f32_e32 v2, v56, v3
	v_cvt_pk_bf16_f32 v2, v2, v115
	ds_read_b32 v3, v68 offset:44
	ds_write_b16 v67, v2 offset:2912
	s_waitcnt lgkmcnt(1)
	v_rcp_f32_e32 v3, v3
	s_nop 0
	v_mul_f32_e32 v2, v9, v3
	v_cvt_pk_bf16_f32 v2, v2, v115
	ds_write_b16 v67, v2 offset:2992
	v_mul_f32_e32 v2, v25, v3
	v_cvt_pk_bf16_f32 v2, v2, v115
	ds_write_b16 v67, v2 offset:3056
	v_mul_f32_e32 v2, v41, v3
	v_cvt_pk_bf16_f32 v2, v2, v115
	ds_write_b16 v67, v2 offset:3120
	v_mul_f32_e32 v2, v57, v3
	v_cvt_pk_bf16_f32 v2, v2, v115
	ds_read_b32 v3, v68 offset:64
	ds_write_b16 v67, v2 offset:3184
	s_waitcnt lgkmcnt(1)
	v_rcp_f32_e32 v3, v3
	s_nop 0
	v_mul_f32_e32 v2, v10, v3
	v_cvt_pk_bf16_f32 v2, v2, v115
	ds_write_b16 v67, v2 offset:4352
	v_mul_f32_e32 v2, v26, v3
	v_cvt_pk_bf16_f32 v2, v2, v115
	ds_write_b16 v67, v2 offset:4416
	v_mul_f32_e32 v2, v42, v3
	v_cvt_pk_bf16_f32 v2, v2, v115
	ds_write_b16 v67, v2 offset:4480
	v_mul_f32_e32 v2, v58, v3
	v_cvt_pk_bf16_f32 v2, v2, v115
	ds_read_b32 v3, v68 offset:68
	ds_write_b16 v67, v2 offset:4544
	s_waitcnt lgkmcnt(1)
	v_rcp_f32_e32 v3, v3
	s_nop 0
	v_mul_f32_e32 v2, v11, v3
	v_cvt_pk_bf16_f32 v2, v2, v115
	ds_write_b16 v67, v2 offset:4624
	v_mul_f32_e32 v2, v27, v3
	v_cvt_pk_bf16_f32 v2, v2, v115
	ds_write_b16 v67, v2 offset:4688
	v_mul_f32_e32 v2, v43, v3
	v_cvt_pk_bf16_f32 v2, v2, v115
	ds_write_b16 v67, v2 offset:4752
	v_mul_f32_e32 v2, v59, v3
	v_cvt_pk_bf16_f32 v2, v2, v115
	ds_read_b32 v3, v68 offset:72
	ds_write_b16 v67, v2 offset:4816
	s_waitcnt lgkmcnt(1)
	v_rcp_f32_e32 v3, v3
	s_nop 0
	v_mul_f32_e32 v2, v12, v3
	v_cvt_pk_bf16_f32 v2, v2, v115
	ds_write_b16 v67, v2 offset:4896
	v_mul_f32_e32 v2, v28, v3
	v_cvt_pk_bf16_f32 v2, v2, v115
	ds_write_b16 v67, v2 offset:4960
	v_mul_f32_e32 v2, v44, v3
	v_cvt_pk_bf16_f32 v2, v2, v115
	ds_write_b16 v67, v2 offset:5024
	v_mul_f32_e32 v2, v60, v3
	v_cvt_pk_bf16_f32 v2, v2, v115
	ds_read_b32 v3, v68 offset:76
	ds_write_b16 v67, v2 offset:5088
	s_waitcnt lgkmcnt(1)
; __device__ __forceinline__ float bf_lo(unsigned w) { return __uint_as_float(w << 16); }
; __device__ __forceinline__ float bf_hi(unsigned w) { return __uint_as_float(w & 0xffff0000u); }
; __device__ __forceinline__ unsigned cvt_pk_bf16(float lo, float hi) { unsigned r; asm volatile("v_cvt_pk_bf16_f32 %0, %1, %2" : "=v"(r) : "v"(lo), "v"(hi)); return r; }
; __device__ __forceinline__ bf16_t f2bf(float f) { return (bf16_t)(cvt_pk_bf16(f, 0.f) & 0xffffu); }
; __device__ __forceinline__ int crow(int r, int hi) { return (r & 3) + 8 * (r >> 2) + 4 * hi; }
; __device__ __forceinline__ void attn_unit_dma(const bf16_t* __restrict__ Qb, const bf16_t* __restrict__ Kh, const bf16_t* __restrict__ Vh, int seq, char* lds, LAS unsigned char* ldsl, ...
;     ...
;     for (int r = 0; r < 16; ++r) { const int rw = crow(r, hi); const float rl = __builtin_amdgcn_rcpf(li_l[rw]);
; #pragma unroll
;       for (int d0 = 0; d0 < 4; ++d0) *(bf16_t*)(Ost + rw * RS + (d0 * 32 + r32) * 2) = f2bf(o[d0][r] * rl); }
;     asm volatile("s_waitcnt lgkmcnt(0)" ::: "memory");
; #pragma unroll
;     for (int i = 0; i < 8; ++i) { const int q = lane + 64 * i, row = q >> 4, cc = q & 15; const long orow = wid * QBLK + row;
;       const u32x4 ov = *(const u32x4*)(Ost + row * RS + cc * 16); const u32x4 gv = *(const u32x4*)(gate + orow * NZ + cc * 8);
;       u32x4 w; w.x = cvt_pk_bf16(bf_lo(ov.x) * bf_lo(gv.x), bf_hi(ov.x) * bf_hi(gv.x)); w.y = cvt_pk_bf16(bf_lo(ov.y) * bf_lo(gv.y), bf_hi(ov.y) * bf_hi(gv.y));
;       w.z = cvt_pk_bf16(bf_lo(ov.z) * bf_lo(gv.z), bf_hi(ov.z) * bf_hi(gv.z)); w.w = cvt_pk_bf16(bf_lo(ov.w) * bf_lo(gv.w), bf_hi(ov.w) * bf_hi(gv.w));
;       *(u32x4*)(Yo + orow * 4096 + cc * 8) = w; }
	v_rcp_f32_e32 v3, v3
	s_nop 0
	v_mul_f32_e32 v2, v13, v3
	v_cvt_pk_bf16_f32 v2, v2, v115
	ds_write_b16 v67, v2 offset:5168
	v_mul_f32_e32 v2, v29, v3
	v_cvt_pk_bf16_f32 v2, v2, v115
	ds_write_b16 v67, v2 offset:5232
	v_mul_f32_e32 v2, v45, v3
	v_cvt_pk_bf16_f32 v2, v2, v115
	ds_write_b16 v67, v2 offset:5296
	v_mul_f32_e32 v2, v61, v3
	v_cvt_pk_bf16_f32 v2, v2, v115
	ds_read_b32 v3, v68 offset:96
	ds_write_b16 v67, v2 offset:5360
	s_waitcnt lgkmcnt(1)
	v_rcp_f32_e32 v3, v3
	s_nop 0
	v_mul_f32_e32 v2, v14, v3
	v_cvt_pk_bf16_f32 v2, v2, v115
	ds_write_b16 v67, v2 offset:6528
	v_mul_f32_e32 v2, v30, v3
	v_cvt_pk_bf16_f32 v2, v2, v115
	ds_write_b16 v67, v2 offset:6592
	v_mul_f32_e32 v2, v46, v3
	v_cvt_pk_bf16_f32 v2, v2, v115
	ds_write_b16 v67, v2 offset:6656
	v_mul_f32_e32 v2, v62, v3
	v_cvt_pk_bf16_f32 v2, v2, v115
	ds_read_b32 v3, v68 offset:100
	ds_write_b16 v67, v2 offset:6720
	s_waitcnt lgkmcnt(1)
	v_rcp_f32_e32 v3, v3
	s_nop 0
	v_mul_f32_e32 v2, v15, v3
	v_cvt_pk_bf16_f32 v2, v2, v115
	ds_write_b16 v67, v2 offset:6800
	v_mul_f32_e32 v2, v31, v3
	v_cvt_pk_bf16_f32 v2, v2, v115
	ds_write_b16 v67, v2 offset:6864
	v_mul_f32_e32 v2, v47, v3
	v_cvt_pk_bf16_f32 v2, v2, v115
	ds_write_b16 v67, v2 offset:6928
	v_mul_f32_e32 v2, v63, v3
	v_cvt_pk_bf16_f32 v2, v2, v115
	ds_read_b32 v3, v68 offset:104
	ds_write_b16 v67, v2 offset:6992
	s_waitcnt lgkmcnt(1)
	v_rcp_f32_e32 v3, v3
	s_nop 0
	v_mul_f32_e32 v2, v16, v3
	v_cvt_pk_bf16_f32 v2, v2, v115
	ds_write_b16 v67, v2 offset:7072
	v_mul_f32_e32 v2, v32, v3
	v_cvt_pk_bf16_f32 v2, v2, v115
	ds_write_b16 v67, v2 offset:7136
	v_mul_f32_e32 v2, v48, v3
	v_cvt_pk_bf16_f32 v2, v2, v115
	ds_write_b16 v67, v2 offset:7200
	v_mul_f32_e32 v2, v64, v3
	v_cvt_pk_bf16_f32 v2, v2, v115
	ds_read_b32 v3, v68 offset:108
	ds_write_b16 v67, v2 offset:7264
	s_waitcnt lgkmcnt(1)
	v_rcp_f32_e32 v3, v3
	s_nop 0
	v_mul_f32_e32 v2, v17, v3
	v_cvt_pk_bf16_f32 v2, v2, v115
	ds_write_b16 v67, v2 offset:7344
	v_mul_f32_e32 v2, v33, v3
	v_cvt_pk_bf16_f32 v2, v2, v115
	ds_write_b16 v67, v2 offset:7408
	v_mul_f32_e32 v2, v49, v3
	v_cvt_pk_bf16_f32 v2, v2, v115
	ds_write_b16 v67, v2 offset:7472
	v_mul_f32_e32 v2, v65, v3
	v_cvt_pk_bf16_f32 v2, v2, v115
	ds_write_b16 v67, v2 offset:7536
	v_lshlrev_b32_e32 v2, 4, v66
	v_and_b32_e32 v114, 0xf0, v2
	v_lshl_add_u64 v[2:3], s[6:7], 0, v[114:115]
	s_mov_b64 s[6:7], 0x1c00
	v_lshl_add_u64 v[2:3], v[2:3], 0, s[6:7]
	s_waitcnt lgkmcnt(0)
	v_mad_i64_i32 v[6:7], s[6:7], v4, s42, v[2:3]
	s_mov_b64 s[98:99], 0x29000
	global_load_dwordx4 v[30:33], v[6:7], off
	v_lshl_add_u64 v[62:63], v[6:7], 0, s[98:99]
	global_load_dwordx4 v[34:37], v[62:63], off
	v_lshl_add_u64 v[62:63], v[62:63], 0, s[98:99]
	global_load_dwordx4 v[38:41], v[62:63], off
	v_lshl_add_u64 v[62:63], v[62:63], 0, s[98:99]
	global_load_dwordx4 v[42:45], v[62:63], off
	v_lshl_add_u64 v[62:63], v[62:63], 0, s[98:99]
	global_load_dwordx4 v[46:49], v[62:63], off
	v_lshl_add_u64 v[62:63], v[62:63], 0, s[98:99]
	global_load_dwordx4 v[50:53], v[62:63], off
	v_lshl_add_u64 v[62:63], v[62:63], 0, s[98:99]
	global_load_dwordx4 v[54:57], v[62:63], off
	v_lshl_add_u64 v[62:63], v[62:63], 0, s[98:99]
	global_load_dwordx4 v[58:61], v[62:63], off
	v_add3_u32 v8, v71, v114, v5
	ds_read_b128 v[14:17], v8
	v_mad_i64_i32 v[6:7], s[6:7], v22, s42, v[2:3]
	s_lshl_b64 s[6:7], s[20:21], 13
	s_add_u32 s6, s78, s6
	s_waitcnt lgkmcnt(0)
	v_lshlrev_b32_e32 v5, 16, v14
	v_and_b32_e32 v9, 0xffff0000, v14
	v_lshlrev_b32_e32 v14, 16, v15
	v_and_b32_e32 v15, 0xffff0000, v15
	v_lshlrev_b32_e32 v18, 16, v16
	v_and_b32_e32 v16, 0xffff0000, v16
	v_lshlrev_b32_e32 v19, 16, v17
	v_and_b32_e32 v17, 0xffff0000, v17
	s_addc_u32 s7, s79, s7
	s_add_u32 s6, s6, s10
	s_addc_u32 s7, s7, 0
	s_add_i32 s12, s12, 1
	s_waitcnt vmcnt(7)
	v_mov_b32_e32 v10, v30
	v_mov_b32_e32 v11, v31
	v_mov_b32_e32 v12, v32
	v_mov_b32_e32 v13, v33
	v_lshlrev_b32_e32 v21, 16, v11
	v_and_b32_e32 v11, 0xffff0000, v11
	v_lshlrev_b32_e32 v23, 16, v12
	v_and_b32_e32 v12, 0xffff0000, v12
	v_lshlrev_b32_e32 v24, 16, v13
	v_and_b32_e32 v13, 0xffff0000, v13
	v_lshlrev_b32_e32 v20, 16, v10
	v_and_b32_e32 v10, 0xffff0000, v10
	v_mul_f32_e32 v14, v21, v14
	v_mul_f32_e32 v11, v11, v15
	v_mul_f32_e32 v15, v23, v18
	v_mul_f32_e32 v12, v12, v16
	v_mul_f32_e32 v16, v24, v19
	v_mul_f32_e32 v13, v13, v17
	v_mul_f32_e32 v5, v20, v5
	v_mul_f32_e32 v9, v10, v9
	v_cvt_pk_bf16_f32 v10, v5, v9
	v_cvt_pk_bf16_f32 v11, v14, v11
	v_cvt_pk_bf16_f32 v12, v15, v12
	v_cvt_pk_bf16_f32 v13, v16, v13
	ds_read_b128 v[18:21], v8 offset:1088
	v_ashrrev_i32_e32 v5, 31, v4
	v_lshlrev_b64 v[26:27], 13, v[4:5]
	v_lshl_add_u64 v[6:7], s[6:7], 0, v[114:115]
	v_lshl_add_u64 v[26:27], v[6:7], 0, v[26:27]
	v_or_b32_e32 v24, 8, v4
	global_store_dwordx4 v[26:27], v[10:13], off offset:2048
	s_waitcnt lgkmcnt(0)
	v_lshlrev_b32_e32 v5, 16, v18
	v_and_b32_e32 v9, 0xffff0000, v18
	v_lshlrev_b32_e32 v10, 16, v19
	v_and_b32_e32 v11, 0xffff0000, v19
	v_lshlrev_b32_e32 v12, 16, v20
	v_and_b32_e32 v13, 0xffff0000, v20
	v_lshlrev_b32_e32 v18, 16, v21
	v_and_b32_e32 v19, 0xffff0000, v21
	v_mad_i64_i32 v[28:29], s[10:11], v24, s42, v[2:3]
	v_or_b32_e32 v26, 12, v4
	v_ashrrev_i32_e32 v27, 31, v26
	s_waitcnt vmcnt(7)
; __device__ __forceinline__ float bf_lo(unsigned w) { return __uint_as_float(w << 16); }
; __device__ __forceinline__ float bf_hi(unsigned w) { return __uint_as_float(w & 0xffff0000u); }
; __device__ __forceinline__ unsigned cvt_pk_bf16(float lo, float hi) { unsigned r; asm volatile("v_cvt_pk_bf16_f32 %0, %1, %2" : "=v"(r) : "v"(lo), "v"(hi)); return r; }
; __device__ __forceinline__ void attn_unit_dma(const bf16_t* __restrict__ Qb, const bf16_t* __restrict__ Kh, const bf16_t* __restrict__ Vh, int seq, char* lds, LAS unsigned char* ldsl, ...
;     ...
;     for (int i = 0; i < 8; ++i) { const int q = lane + 64 * i, row = q >> 4, cc = q & 15; const long orow = wid * QBLK + row;
;       const u32x4 ov = *(const u32x4*)(Ost + row * RS + cc * 16); const u32x4 gv = *(const u32x4*)(gate + orow * NZ + cc * 8);
;       u32x4 w; w.x = cvt_pk_bf16(bf_lo(ov.x) * bf_lo(gv.x), bf_hi(ov.x) * bf_hi(gv.x)); w.y = cvt_pk_bf16(bf_lo(ov.y) * bf_lo(gv.y), bf_hi(ov.y) * bf_hi(gv.y));
;       w.z = cvt_pk_bf16(bf_lo(ov.z) * bf_lo(gv.z), bf_hi(ov.z) * bf_hi(gv.z)); w.w = cvt_pk_bf16(bf_lo(ov.w) * bf_lo(gv.w), bf_hi(ov.w) * bf_hi(gv.w));
;       *(u32x4*)(Yo + orow * 4096 + cc * 8) = w; }
	v_mov_b32_e32 v14, v34
	v_mov_b32_e32 v15, v35
	v_mov_b32_e32 v16, v36
	v_mov_b32_e32 v17, v37
	v_lshlrev_b32_e32 v20, 16, v14
	v_and_b32_e32 v14, 0xffff0000, v14
	v_lshlrev_b32_e32 v21, 16, v15
	v_and_b32_e32 v15, 0xffff0000, v15
	v_lshlrev_b32_e32 v23, 16, v16
	v_and_b32_e32 v16, 0xffff0000, v16
	v_lshlrev_b32_e32 v25, 16, v17
	v_and_b32_e32 v17, 0xffff0000, v17
	v_mul_f32_e32 v9, v14, v9
	v_mul_f32_e32 v14, v21, v10
	v_mul_f32_e32 v11, v15, v11
	v_mul_f32_e32 v12, v23, v12
	v_mul_f32_e32 v13, v16, v13
	v_mul_f32_e32 v15, v25, v18
	v_mul_f32_e32 v16, v17, v19
	v_mul_f32_e32 v5, v20, v5
	v_cvt_pk_bf16_f32 v10, v5, v9
	v_cvt_pk_bf16_f32 v11, v14, v11
	v_cvt_pk_bf16_f32 v12, v12, v13
	v_cvt_pk_bf16_f32 v13, v15, v16
	ds_read_b128 v[18:21], v8 offset:2176
	v_ashrrev_i32_e32 v23, 31, v22
	v_lshlrev_b64 v[22:23], 13, v[22:23]
	v_lshl_add_u64 v[22:23], v[6:7], 0, v[22:23]
	global_store_dwordx4 v[22:23], v[10:13], off offset:2048
	s_waitcnt lgkmcnt(0)
	v_lshlrev_b32_e32 v5, 16, v18
	v_and_b32_e32 v9, 0xffff0000, v18
	v_lshlrev_b32_e32 v10, 16, v19
	v_and_b32_e32 v11, 0xffff0000, v19
	v_lshlrev_b32_e32 v12, 16, v20
	v_and_b32_e32 v13, 0xffff0000, v20
	v_lshlrev_b32_e32 v18, 16, v21
	v_and_b32_e32 v19, 0xffff0000, v21
	v_mad_i64_i32 v[28:29], s[6:7], v26, s42, v[2:3]
	v_ashrrev_i32_e32 v25, 31, v24
	v_lshlrev_b64 v[24:25], 13, v[24:25]
	v_lshl_add_u64 v[24:25], v[6:7], 0, v[24:25]
	v_lshlrev_b64 v[26:27], 13, v[26:27]
	v_lshl_add_u64 v[26:27], v[6:7], 0, v[26:27]
	s_waitcnt vmcnt(7)
	v_mov_b32_e32 v14, v38
	v_mov_b32_e32 v15, v39
	v_mov_b32_e32 v16, v40
	v_mov_b32_e32 v17, v41
	v_lshlrev_b32_e32 v20, 16, v14
	v_and_b32_e32 v14, 0xffff0000, v14
	v_lshlrev_b32_e32 v21, 16, v15
	v_and_b32_e32 v15, 0xffff0000, v15
	v_lshlrev_b32_e32 v22, 16, v16
	v_and_b32_e32 v16, 0xffff0000, v16
	v_lshlrev_b32_e32 v23, 16, v17
	v_and_b32_e32 v17, 0xffff0000, v17
	v_mul_f32_e32 v9, v14, v9
	v_mul_f32_e32 v14, v21, v10
	v_mul_f32_e32 v11, v15, v11
	v_mul_f32_e32 v12, v22, v12
	v_mul_f32_e32 v13, v16, v13
	v_mul_f32_e32 v15, v23, v18
	v_mul_f32_e32 v16, v17, v19
	v_mul_f32_e32 v5, v20, v5
	v_cvt_pk_bf16_f32 v10, v5, v9
	v_cvt_pk_bf16_f32 v11, v14, v11
	v_cvt_pk_bf16_f32 v12, v12, v13
	v_cvt_pk_bf16_f32 v13, v15, v16
	ds_read_b128 v[18:21], v8 offset:3264
	v_or_b32_e32 v22, 16, v4
	global_store_dwordx4 v[24:25], v[10:13], off offset:2048
	v_mad_i64_i32 v[28:29], s[6:7], v22, s42, v[2:3]
	s_waitcnt lgkmcnt(0)
	v_lshlrev_b32_e32 v5, 16, v18
	v_and_b32_e32 v9, 0xffff0000, v18
	v_lshlrev_b32_e32 v10, 16, v19
	v_and_b32_e32 v11, 0xffff0000, v19
	v_lshlrev_b32_e32 v12, 16, v20
	v_and_b32_e32 v13, 0xffff0000, v20
	v_lshlrev_b32_e32 v18, 16, v21
	v_and_b32_e32 v19, 0xffff0000, v21
	s_waitcnt vmcnt(7)
	v_mov_b32_e32 v14, v42
	v_mov_b32_e32 v15, v43
	v_mov_b32_e32 v16, v44
	v_mov_b32_e32 v17, v45
	v_lshlrev_b32_e32 v20, 16, v14
	v_and_b32_e32 v14, 0xffff0000, v14
	v_lshlrev_b32_e32 v21, 16, v15
	v_and_b32_e32 v15, 0xffff0000, v15
	v_lshlrev_b32_e32 v23, 16, v16
	v_and_b32_e32 v16, 0xffff0000, v16
	v_lshlrev_b32_e32 v24, 16, v17
	v_and_b32_e32 v17, 0xffff0000, v17
	v_mul_f32_e32 v9, v14, v9
	v_mul_f32_e32 v14, v21, v10
	v_mul_f32_e32 v11, v15, v11
	v_mul_f32_e32 v12, v23, v12
	v_mul_f32_e32 v13, v16, v13
	v_mul_f32_e32 v15, v24, v18
	v_mul_f32_e32 v16, v17, v19
	v_mul_f32_e32 v5, v20, v5
	v_cvt_pk_bf16_f32 v10, v5, v9
	v_cvt_pk_bf16_f32 v11, v14, v11
	v_cvt_pk_bf16_f32 v12, v12, v13
	v_cvt_pk_bf16_f32 v13, v15, v16
	ds_read_b128 v[18:21], v8 offset:4352
	v_or_b32_e32 v24, 20, v4
	global_store_dwordx4 v[26:27], v[10:13], off offset:2048
	v_mad_i64_i32 v[28:29], s[6:7], v24, s42, v[2:3]
	s_waitcnt lgkmcnt(0)
	v_lshlrev_b32_e32 v5, 16, v18
	v_and_b32_e32 v9, 0xffff0000, v18
	v_lshlrev_b32_e32 v10, 16, v19
	v_and_b32_e32 v11, 0xffff0000, v19
	v_lshlrev_b32_e32 v12, 16, v20
	v_and_b32_e32 v13, 0xffff0000, v20
	v_lshlrev_b32_e32 v18, 16, v21
	v_and_b32_e32 v19, 0xffff0000, v21
	v_or_b32_e32 v26, 24, v4
	v_ashrrev_i32_e32 v27, 31, v26
	s_waitcnt vmcnt(7)
; __device__ __forceinline__ float bf_lo(unsigned w) { return __uint_as_float(w << 16); }
; __device__ __forceinline__ float bf_hi(unsigned w) { return __uint_as_float(w & 0xffff0000u); }
; __device__ __forceinline__ unsigned cvt_pk_bf16(float lo, float hi) { unsigned r; asm volatile("v_cvt_pk_bf16_f32 %0, %1, %2" : "=v"(r) : "v"(lo), "v"(hi)); return r; }
; __device__ __forceinline__ void attn_unit_dma(const bf16_t* __restrict__ Qb, const bf16_t* __restrict__ Kh, const bf16_t* __restrict__ Vh, int seq, char* lds, LAS unsigned char* ldsl, ...
;     ...
;     for (int i = 0; i < 8; ++i) { const int q = lane + 64 * i, row = q >> 4, cc = q & 15; const long orow = wid * QBLK + row;
;       const u32x4 ov = *(const u32x4*)(Ost + row * RS + cc * 16); const u32x4 gv = *(const u32x4*)(gate + orow * NZ + cc * 8);
;       u32x4 w; w.x = cvt_pk_bf16(bf_lo(ov.x) * bf_lo(gv.x), bf_hi(ov.x) * bf_hi(gv.x)); w.y = cvt_pk_bf16(bf_lo(ov.y) * bf_lo(gv.y), bf_hi(ov.y) * bf_hi(gv.y));
;       w.z = cvt_pk_bf16(bf_lo(ov.z) * bf_lo(gv.z), bf_hi(ov.z) * bf_hi(gv.z)); w.w = cvt_pk_bf16(bf_lo(ov.w) * bf_lo(gv.w), bf_hi(ov.w) * bf_hi(gv.w));
;       *(u32x4*)(Yo + orow * 4096 + cc * 8) = w; }
;   }
;   __syncthreads();
	v_mov_b32_e32 v14, v46
	v_mov_b32_e32 v15, v47
	v_mov_b32_e32 v16, v48
	v_mov_b32_e32 v17, v49
	v_lshlrev_b32_e32 v20, 16, v14
	v_and_b32_e32 v14, 0xffff0000, v14
	v_lshlrev_b32_e32 v21, 16, v15
	v_and_b32_e32 v15, 0xffff0000, v15
	v_lshlrev_b32_e32 v23, 16, v16
	v_and_b32_e32 v16, 0xffff0000, v16
	v_lshlrev_b32_e32 v25, 16, v17
	v_and_b32_e32 v17, 0xffff0000, v17
	v_mul_f32_e32 v9, v14, v9
	v_mul_f32_e32 v14, v21, v10
	v_mul_f32_e32 v11, v15, v11
	v_mul_f32_e32 v12, v23, v12
	v_mul_f32_e32 v13, v16, v13
	v_mul_f32_e32 v15, v25, v18
	v_mul_f32_e32 v16, v17, v19
	v_mul_f32_e32 v5, v20, v5
	v_cvt_pk_bf16_f32 v10, v5, v9
	v_cvt_pk_bf16_f32 v11, v14, v11
	v_cvt_pk_bf16_f32 v12, v12, v13
	v_cvt_pk_bf16_f32 v13, v15, v16
	ds_read_b128 v[18:21], v8 offset:5440
	v_ashrrev_i32_e32 v23, 31, v22
	v_lshlrev_b64 v[22:23], 13, v[22:23]
	v_lshl_add_u64 v[22:23], v[6:7], 0, v[22:23]
	global_store_dwordx4 v[22:23], v[10:13], off offset:2048
	s_waitcnt lgkmcnt(0)
	v_lshlrev_b32_e32 v5, 16, v18
	v_and_b32_e32 v9, 0xffff0000, v18
	v_lshlrev_b32_e32 v10, 16, v19
	v_and_b32_e32 v11, 0xffff0000, v19
	v_lshlrev_b32_e32 v12, 16, v20
	v_and_b32_e32 v13, 0xffff0000, v20
	v_lshlrev_b32_e32 v18, 16, v21
	v_and_b32_e32 v19, 0xffff0000, v21
	v_mad_i64_i32 v[28:29], s[6:7], v26, s42, v[2:3]
	v_ashrrev_i32_e32 v25, 31, v24
	s_waitcnt vmcnt(7)
	v_mov_b32_e32 v14, v50
	v_mov_b32_e32 v15, v51
	v_mov_b32_e32 v16, v52
	v_mov_b32_e32 v17, v53
	v_lshlrev_b32_e32 v20, 16, v14
	v_and_b32_e32 v14, 0xffff0000, v14
	v_lshlrev_b32_e32 v21, 16, v15
	v_and_b32_e32 v15, 0xffff0000, v15
	v_lshlrev_b32_e32 v22, 16, v16
	v_and_b32_e32 v16, 0xffff0000, v16
	v_lshlrev_b32_e32 v23, 16, v17
	v_and_b32_e32 v17, 0xffff0000, v17
	v_mul_f32_e32 v9, v14, v9
	v_mul_f32_e32 v14, v21, v10
	v_mul_f32_e32 v11, v15, v11
	v_mul_f32_e32 v12, v22, v12
	v_mul_f32_e32 v13, v16, v13
	v_mul_f32_e32 v15, v23, v18
	v_mul_f32_e32 v16, v17, v19
	v_mul_f32_e32 v5, v20, v5
	v_cvt_pk_bf16_f32 v10, v5, v9
	v_cvt_pk_bf16_f32 v11, v14, v11
	v_cvt_pk_bf16_f32 v12, v12, v13
	v_cvt_pk_bf16_f32 v13, v15, v16
	ds_read_b128 v[18:21], v8 offset:6528
	v_or_b32_e32 v22, 28, v4
	v_lshlrev_b64 v[4:5], 13, v[24:25]
	v_mad_i64_i32 v[24:25], s[6:7], v22, s42, v[2:3]
	v_lshl_add_u64 v[2:3], v[6:7], 0, v[4:5]
	global_store_dwordx4 v[2:3], v[10:13], off offset:2048
	s_waitcnt lgkmcnt(0)
	v_lshlrev_b32_e32 v2, 16, v18
	v_and_b32_e32 v3, 0xffff0000, v18
	v_lshlrev_b32_e32 v4, 16, v19
	v_and_b32_e32 v5, 0xffff0000, v19
	v_lshlrev_b32_e32 v9, 16, v20
	v_and_b32_e32 v10, 0xffff0000, v20
	v_lshlrev_b32_e32 v11, 16, v21
	v_and_b32_e32 v12, 0xffff0000, v21
	v_ashrrev_i32_e32 v23, 31, v22
	s_mul_i32 s6, s12, s56
	s_add_i32 s10, s6, s2
	s_cmp_ge_i32 s10, s38
	s_waitcnt vmcnt(7)
	v_mov_b32_e32 v14, v54
	v_mov_b32_e32 v15, v55
	v_mov_b32_e32 v16, v56
	v_mov_b32_e32 v17, v57
	v_lshlrev_b32_e32 v13, 16, v14
	v_and_b32_e32 v14, 0xffff0000, v14
	v_lshlrev_b32_e32 v18, 16, v15
	v_and_b32_e32 v15, 0xffff0000, v15
	v_lshlrev_b32_e32 v19, 16, v16
	v_and_b32_e32 v16, 0xffff0000, v16
	v_lshlrev_b32_e32 v20, 16, v17
	v_and_b32_e32 v17, 0xffff0000, v17
	v_mul_f32_e32 v2, v13, v2
	v_mul_f32_e32 v3, v14, v3
	v_mul_f32_e32 v4, v18, v4
	v_mul_f32_e32 v5, v15, v5
	v_mul_f32_e32 v10, v16, v10
	v_mul_f32_e32 v11, v20, v11
	v_mul_f32_e32 v12, v17, v12
	v_mul_f32_e32 v9, v19, v9
	v_cvt_pk_bf16_f32 v2, v2, v3
	v_cvt_pk_bf16_f32 v3, v4, v5
	v_cvt_pk_bf16_f32 v4, v9, v10
	v_cvt_pk_bf16_f32 v5, v11, v12
	v_lshlrev_b64 v[14:15], 13, v[26:27]
	v_lshl_add_u64 v[20:21], v[6:7], 0, v[14:15]
	ds_read_b128 v[14:17], v8 offset:7616
	v_lshlrev_b64 v[18:19], 13, v[22:23]
	global_store_dwordx4 v[20:21], v[2:5], off offset:2048
	v_lshl_add_u64 v[6:7], v[6:7], 0, v[18:19]
	s_waitcnt lgkmcnt(0)
	v_lshlrev_b32_e32 v8, 16, v16
	v_lshlrev_b32_e32 v2, 16, v14
	v_and_b32_e32 v3, 0xffff0000, v14
	v_lshlrev_b32_e32 v4, 16, v15
	v_and_b32_e32 v5, 0xffff0000, v15
	v_and_b32_e32 v9, 0xffff0000, v16
	v_lshlrev_b32_e32 v14, 16, v17
	v_and_b32_e32 v15, 0xffff0000, v17
	s_waitcnt vmcnt(7)
	v_mov_b32_e32 v10, v58
	v_mov_b32_e32 v11, v59
	v_mov_b32_e32 v12, v60
	v_mov_b32_e32 v13, v61
	v_lshlrev_b32_e32 v16, 16, v10
	v_and_b32_e32 v10, 0xffff0000, v10
	v_lshlrev_b32_e32 v17, 16, v11
	v_and_b32_e32 v11, 0xffff0000, v11
	v_lshlrev_b32_e32 v18, 16, v12
	v_and_b32_e32 v12, 0xffff0000, v12
	v_lshlrev_b32_e32 v19, 16, v13
	v_and_b32_e32 v13, 0xffff0000, v13
	v_mul_f32_e32 v2, v16, v2
	v_mul_f32_e32 v3, v10, v3
	v_mul_f32_e32 v4, v17, v4
	v_mul_f32_e32 v5, v11, v5
	v_mul_f32_e32 v8, v18, v8
	v_mul_f32_e32 v9, v12, v9
	v_mul_f32_e32 v10, v19, v14
	v_mul_f32_e32 v11, v13, v15
	v_cvt_pk_bf16_f32 v2, v2, v3
	v_cvt_pk_bf16_f32 v3, v4, v5
	v_cvt_pk_bf16_f32 v4, v8, v9
	v_cvt_pk_bf16_f32 v5, v10, v11
	global_store_dwordx4 v[6:7], v[2:5], off offset:2048
	s_barrier
	s_cbranch_scc1 .LBB0_871
